# m10 plus software-pipelined residual-update row loop (phases 3/8) and hoisted per-k gain loads in the phase-0 transposes
# baseline (speedup 1.0000x reference)
; #define SCHED_FENCE() __builtin_amdgcn_sched_barrier(0)
; __device__ __forceinline__ float bflo(unsigned u) { return __uint_as_float(u << 16); }
; __device__ __forceinline__ float bfhi(unsigned u) { return __uint_as_float(u & 0xffff0000u); }
; #define PH_LAUNDER() int tid = wave0 * 64 + (int)__builtin_amdgcn_mbcnt_hi(~0u, __builtin_amdgcn_mbcnt_lo(~0u, 0u)); asm volatile("" : "+v"(tid)); \
;         const int lane = tid & 63, wave = wave0, gw = bid * 8 + wave; (void)lane; (void)gw
; template <bool FINAL>
; __device__ __forceinline__ void resid_row(const bf16_t* f, bf16_t* h, const f32x4 (&gp)[8], float alpha, float* rs_out, const f32x4 (&gn)[8], float* fin, int lane) {
;     u32x2 wf[8], wh[8];
; #pragma unroll
;     for (int j = 0; j < 8; ++j) { wf[j] = *(const u32x2*)(f + 256 * j + 4 * lane); wh[j] = *(const u32x2*)(h + 256 * j + 4 * lane); }
;     SCHED_FENCE();
;     f32x4 v[8]; float s = 0.f;
; #pragma unroll
;     for (int j = 0; j < 8; ++j) { v[j] = (f32x4){bflo(wf[j].x), bfhi(wf[j].x), bflo(wf[j].y), bfhi(wf[j].y)};
;         s += (v[j].x * v[j].x + v[j].y * v[j].y) + (v[j].z * v[j].z + v[j].w * v[j].w); }
;     const float rs = rsqrtf(wave_sum(s, lane) * (1.0f / DM) + EPS) * alpha;
; __global__ void __launch_bounds__(512, 2) fwd_kernel(Args a) {
;     ...
;         } else if (ph == 3 || ph == 8 || ph == 11) {
;             PH_LAUNDER();
;             const float* gpp = a.in[ph == 3 ? 5 : ph == 8 ? 19 : 23];
;             const float* gnp = a.in[24];
;             f32x4 gp[8], gn[8];
; #pragma unroll
;             for (int j = 0; j < 8; ++j) { gp[j] = *(const f32x4*)(gpp + 256 * j + 4 * lane); gn[j] = *(const f32x4*)(gnp + 256 * j + 4 * lane); }
;             if (ph == 11) { for (int m = gw; m < MTOK; m += ngw) resid_row<true>(F + (size_t)m * DM, XN + (size_t)m * DM, gp, 0.5f, nullptr, gn, P.out + (size_t)m * DM, lane); }
;             else { const float alpha = ph == 3 ? 0.5f : 1.0f;
;                 for (int m = gw; m < MTOK; m += ngw) resid_row<false>(F + (size_t)m * DM, XN + (size_t)m * DM, gp, alpha, RS + m, gn, nullptr, lane); }
.LBB0_241:
	s_and_b64 vcc, exec, s[40:41]
	s_mov_b64 s[40:41], s[50:51]
	s_cbranch_vccz .LBB0_253
	s_cmp_eq_u32 s68, 8
	s_cselect_b32 s10, 19, 23
	s_cmp_eq_u32 s68, 3
	s_cselect_b64 s[6:7], -1, 0
	s_and_b64 s[8:9], s[6:7], exec
	s_cselect_b32 s8, 5, s10
	s_lshl_b32 s8, s8, 3
	s_waitcnt vmcnt(0)
	v_mov_b32_e32 v0, v212
	s_load_dwordx2 s[8:9], s[40:41], s8 offset:0x0
	v_and_b32_e32 v66, 63, v0
	v_lshlrev_b32_e32 v144, 4, v66
	s_waitcnt lgkmcnt(0)
	global_load_dwordx4 v[0:3], v144, s[8:9]
	global_load_dwordx4 v[4:7], v144, s[8:9] offset:1024
	global_load_dwordx4 v[8:11], v144, s[8:9] offset:2048
	global_load_dwordx4 v[12:15], v144, s[8:9] offset:3072
	v_lshl_add_u64 v[16:17], s[8:9], 0, v[144:145]
	v_add_co_u32_e32 v28, vcc, 0x1000, v16
	s_cmp_lg_u32 s68, 11
	s_nop 0
	v_addc_co_u32_e32 v29, vcc, 0, v17, vcc
	global_load_dwordx4 v[16:19], v[28:29], off
	global_load_dwordx4 v[20:23], v[28:29], off offset:1024
	global_load_dwordx4 v[24:27], v[28:29], off offset:2048
	s_nop 0
	global_load_dwordx4 v[28:31], v[28:29], off offset:3072
	v_lshlrev_b32_e32 v64, 2, v66
	s_mov_b64 s[8:9], -1
	s_cbranch_scc0 .LBB0_249
	v_readlane_b32 s0, v252, 42
	v_readlane_b32 s1, v252, 43
	s_andn2_b64 vcc, exec, s[0:1]
	s_cbranch_vccnz .LBB0_248
	v_readlane_b32 s0, v251, 42
	v_cndmask_b32_e64 v60, 1.0, 0.5, s[6:7]
	v_lshlrev_b32_e32 v32, 3, v66
	v_mov_b32_e32 v33, v145
	v_readlane_b32 s1, v251, 43
	v_readlane_b32 s6, v251, 34
	v_readlane_b32 s8, v251, 38
	v_xor_b32_e32 v61, 4, v64
	v_xor_b32_e32 v62, 8, v64
	v_xor_b32_e32 v63, 16, v64
	v_xor_b32_e32 v65, 32, v64
	v_xor_b32_e32 v67, 64, v64
	v_xor_b32_e32 v68, 0x80, v64
	v_cmp_eq_u32_e64 s[38:39], 0, v66
	v_lshl_add_u64 v[32:33], s[0:1], 0, v[32:33]
	v_readlane_b32 s7, v251, 35
	s_mov_b32 s10, s8
	v_readlane_b32 s9, v251, 39
	v_lshl_add_u64 v[192:193], s[66:67], 0, v[32:33]
	v_add_co_u32_e32 v194, vcc, 0x19820000, v192
	s_nop 1
	v_addc_co_u32_e32 v195, vcc, 0, v193, vcc
	v_add_co_u32_e32 v192, vcc, 0xa820000, v192
	s_nop 1
	v_addc_co_u32_e32 v193, vcc, 0, v193, vcc
	global_load_dwordx2 v[160:161], v[194:195], off
	global_load_dwordx2 v[162:163], v[194:195], off offset:512
	global_load_dwordx2 v[164:165], v[194:195], off offset:1024
	global_load_dwordx2 v[166:167], v[194:195], off offset:1536
	global_load_dwordx2 v[168:169], v[192:193], off
	global_load_dwordx2 v[170:171], v[192:193], off offset:512
	global_load_dwordx2 v[172:173], v[192:193], off offset:1024
	global_load_dwordx2 v[174:175], v[192:193], off offset:1536
	global_load_dwordx2 v[176:177], v[194:195], off offset:2048
	global_load_dwordx2 v[178:179], v[194:195], off offset:2560
	global_load_dwordx2 v[180:181], v[194:195], off offset:3072
	global_load_dwordx2 v[182:183], v[194:195], off offset:3584
	global_load_dwordx2 v[184:185], v[192:193], off offset:2048
	global_load_dwordx2 v[186:187], v[192:193], off offset:2560
	global_load_dwordx2 v[188:189], v[192:193], off offset:3072
	global_load_dwordx2 v[190:191], v[192:193], off offset:3584
	s_waitcnt vmcnt(0)
	s_branch .Lr3_copy
.LBB0_245:
	s_or_b64 exec, exec, s[8:9]
	s_add_i32 s10, s10, s46
	s_add_u32 s6, s6, s14
	s_addc_u32 s7, s7, s15
	s_cmpk_gt_i32 s10, 0x3fff
	v_lshl_add_u64 v[32:33], v[32:33], 0, s[16:17]
	s_cbranch_scc1 .LBB0_248
.LBB0_246:
	s_waitcnt vmcnt(9)
.Lr3_copy:
	v_lshl_add_u64 v[34:35], s[66:67], 0, v[32:33]
	s_waitcnt lgkmcnt(0)
	v_add_co_u32_e32 v34, vcc, 0xa820000, v34
	s_nop 1
	v_addc_co_u32_e32 v35, vcc, 0, v35, vcc
	v_mov_b64_e32 v[42:43], v[160:161]
	v_mov_b64_e32 v[44:45], v[162:163]
	v_mov_b64_e32 v[46:47], v[164:165]
	v_mov_b64_e32 v[50:51], v[166:167]
	v_mov_b64_e32 v[56:57], v[168:169]
	v_mov_b64_e32 v[70:71], v[170:171]
	v_mov_b64_e32 v[72:73], v[172:173]
	v_mov_b64_e32 v[54:55], v[174:175]
	v_mov_b64_e32 v[52:53], v[176:177]
	v_mov_b64_e32 v[58:59], v[178:179]
	v_mov_b64_e32 v[74:75], v[180:181]
	v_mov_b64_e32 v[76:77], v[182:183]
	v_mov_b64_e32 v[48:49], v[184:185]
	v_mov_b64_e32 v[40:41], v[186:187]
	v_mov_b64_e32 v[38:39], v[188:189]
	v_mov_b64_e32 v[36:37], v[190:191]
	s_add_i32 s12, s10, s46
	s_cmpk_gt_i32 s12, 0x3fff
	s_cselect_b32 s12, 0, s16
	s_cselect_b32 s13, 0, s17
	v_lshl_add_u64 v[192:193], v[32:33], 0, s[12:13]
	v_lshl_add_u64 v[192:193], s[66:67], 0, v[192:193]
	v_add_co_u32_e32 v194, vcc, 0x19820000, v192
	s_nop 1
	v_addc_co_u32_e32 v195, vcc, 0, v193, vcc
	v_add_co_u32_e32 v192, vcc, 0xa820000, v192
	s_nop 1
	v_addc_co_u32_e32 v193, vcc, 0, v193, vcc
	global_load_dwordx2 v[160:161], v[194:195], off
	global_load_dwordx2 v[162:163], v[194:195], off offset:512
	global_load_dwordx2 v[164:165], v[194:195], off offset:1024
	global_load_dwordx2 v[166:167], v[194:195], off offset:1536
	global_load_dwordx2 v[168:169], v[192:193], off
	global_load_dwordx2 v[170:171], v[192:193], off offset:512
	global_load_dwordx2 v[172:173], v[192:193], off offset:1024
	global_load_dwordx2 v[174:175], v[192:193], off offset:1536
	global_load_dwordx2 v[176:177], v[194:195], off offset:2048
	global_load_dwordx2 v[178:179], v[194:195], off offset:2560
	global_load_dwordx2 v[180:181], v[194:195], off offset:3072
	global_load_dwordx2 v[182:183], v[194:195], off offset:3584
	global_load_dwordx2 v[184:185], v[192:193], off offset:2048
	global_load_dwordx2 v[186:187], v[192:193], off offset:2560
	global_load_dwordx2 v[188:189], v[192:193], off offset:3072
	global_load_dwordx2 v[190:191], v[192:193], off offset:3584
	v_and_b32_e32 v79, 0xffff0000, v42
	v_and_b32_e32 v81, 0xffff0000, v43
	v_lshlrev_b32_e32 v78, 16, v42
	v_lshlrev_b32_e32 v80, 16, v43
	v_mul_f32_e32 v42, v81, v81
	v_and_b32_e32 v85, 0xffff0000, v45
	v_and_b32_e32 v84, 0xffff0000, v44
	v_lshlrev_b32_e32 v86, 16, v46
; __device__ __forceinline__ float bflo(unsigned u) { return __uint_as_float(u << 16); }
; __device__ __forceinline__ float bfhi(unsigned u) { return __uint_as_float(u & 0xffff0000u); }
; __device__ __forceinline__ float shfl_xor_l(float v, int lane, int mask) { return __int_as_float(__builtin_amdgcn_ds_bpermute((lane ^ mask) << 2, __float_as_int(v))); }
; __device__ __forceinline__ float wave_sum(float v, int lane) {
; #pragma unroll
;     for (int o = 1; o < 64; o <<= 1) v += shfl_xor_l(v, lane, o);
;     return v;
; template <bool FINAL>
; __device__ __forceinline__ void resid_row(const bf16_t* f, bf16_t* h, const f32x4 (&gp)[8], float alpha, float* rs_out, const f32x4 (&gn)[8], float* fin, int lane) {
;     ...
;     f32x4 v[8]; float s = 0.f;
; #pragma unroll
;     for (int j = 0; j < 8; ++j) { v[j] = (f32x4){bflo(wf[j].x), bfhi(wf[j].x), bflo(wf[j].y), bfhi(wf[j].y)};
;         s += (v[j].x * v[j].x + v[j].y * v[j].y) + (v[j].z * v[j].z + v[j].w * v[j].w); }
;     const float rs = rsqrtf(wave_sum(s, lane) * (1.0f / DM) + EPS) * alpha;
	v_and_b32_e32 v87, 0xffff0000, v46
	v_mul_f32_e32 v46, v79, v79
	v_pk_fma_f32 v[42:43], v[80:81], v[80:81], v[42:43] op_sel_hi:[1,1,0]
	v_lshlrev_b32_e32 v83, 16, v45
	v_lshlrev_b32_e32 v82, 16, v44
	v_pk_mul_f32 v[44:45], v[84:85], v[84:85]
	v_lshlrev_b32_e32 v88, 16, v47
	v_and_b32_e32 v89, 0xffff0000, v47
	v_lshlrev_b32_e32 v91, 16, v50
	v_pk_fma_f32 v[46:47], v[78:79], v[78:79], v[46:47] op_sel_hi:[1,1,0]
	v_pk_fma_f32 v[44:45], v[82:83], v[82:83], v[44:45]
	v_and_b32_e32 v93, 0xffff0000, v50
	v_lshlrev_b32_e32 v94, 16, v51
	v_and_b32_e32 v95, 0xffff0000, v51
	v_mov_b32_e32 v90, v46
	v_mov_b32_e32 v50, v42
	v_mov_b32_e32 v51, v91
	v_mul_f32_e32 v69, v93, v93
	v_pk_add_f32 v[42:43], v[46:47], v[42:43]
	v_pk_mul_f32 v[46:47], v[90:91], v[50:51]
	v_pk_add_f32 v[44:45], v[44:45], v[44:45] op_sel:[0,1] op_sel_hi:[1,0]
	v_mov_b32_e32 v43, v47
	v_mov_b32_e32 v45, v69
	v_pk_add_f32 v[42:43], v[42:43], v[44:45]
	v_mul_f32_e32 v44, v87, v87
	v_mul_f32_e32 v46, v89, v89
	v_mul_f32_e32 v92, v94, v94
	v_mul_f32_e32 v96, v95, v95
	v_pk_fma_f32 v[44:45], v[86:87], v[86:87], v[44:45] op_sel_hi:[1,1,0]
	v_pk_fma_f32 v[46:47], v[88:89], v[88:89], v[46:47] op_sel_hi:[1,1,0]
	v_mov_b32_e32 v45, v92
	v_mov_b32_e32 v47, v96
	v_pk_add_f32 v[44:45], v[44:45], v[46:47]
	v_and_b32_e32 v101, 0xffff0000, v53
	v_and_b32_e32 v100, 0xffff0000, v52
	v_pk_add_f32 v[96:97], v[42:43], v[44:45]
	v_lshlrev_b32_e32 v99, 16, v53
	v_lshlrev_b32_e32 v98, 16, v52
	v_pk_mul_f32 v[42:43], v[100:101], v[100:101]
	v_and_b32_e32 v107, 0xffff0000, v59
	v_pk_fma_f32 v[42:43], v[98:99], v[98:99], v[42:43]
	v_and_b32_e32 v106, 0xffff0000, v58
	v_pk_add_f32 v[102:103], v[42:43], v[42:43] op_sel:[0,1] op_sel_hi:[1,0]
	v_lshlrev_b32_e32 v105, 16, v59
	v_lshlrev_b32_e32 v104, 16, v58
	v_pk_mul_f32 v[42:43], v[106:107], v[106:107]
	v_lshlrev_b32_e32 v50, 16, v74
	v_and_b32_e32 v51, 0xffff0000, v74
	v_lshlrev_b32_e32 v52, 16, v75
	v_and_b32_e32 v53, 0xffff0000, v75
	v_lshlrev_b32_e32 v47, 16, v76
	v_pk_add_f32 v[74:75], v[96:97], v[96:97] op_sel:[0,1] op_sel_hi:[1,0]
	v_pk_fma_f32 v[58:59], v[104:105], v[104:105], v[42:43]
	v_and_b32_e32 v45, 0xffff0000, v76
	v_lshlrev_b32_e32 v42, 16, v77
	v_and_b32_e32 v43, 0xffff0000, v77
	v_mov_b32_e32 v46, v74
	v_mov_b32_e32 v76, v102
	v_mov_b32_e32 v77, v47
	v_mul_f32_e32 v44, v45, v45
	v_pk_add_f32 v[74:75], v[74:75], v[102:103]
	v_pk_mul_f32 v[76:77], v[46:47], v[76:77]
	v_pk_add_f32 v[58:59], v[58:59], v[58:59] op_sel:[0,1] op_sel_hi:[1,0]
	v_mov_b32_e32 v75, v77
	v_mov_b32_e32 v59, v44
	v_mul_f32_e32 v44, v51, v51
	v_pk_add_f32 v[58:59], v[74:75], v[58:59]
	v_pk_fma_f32 v[74:75], v[50:51], v[50:51], v[44:45] op_sel_hi:[1,1,0]
	v_mul_f32_e32 v44, v53, v53
	v_mul_f32_e32 v69, v42, v42
	v_mul_f32_e32 v90, v43, v43
	v_pk_fma_f32 v[76:77], v[52:53], v[52:53], v[44:45] op_sel_hi:[1,1,0]
	v_mov_b32_e32 v75, v69
	v_mov_b32_e32 v77, v90
	v_pk_add_f32 v[74:75], v[74:75], v[76:77]
	v_mov_b32_e32 v92, v91
	v_pk_add_f32 v[58:59], v[58:59], v[74:75]
	s_nop 0
	v_add_f32_e32 v44, v58, v59
	ds_bpermute_b32 v46, v61, v44
	v_lshlrev_b32_e32 v58, 16, v56
	v_and_b32_e32 v59, 0xffff0000, v56
	v_lshlrev_b32_e32 v56, 16, v57
	v_and_b32_e32 v57, 0xffff0000, v57
	s_waitcnt lgkmcnt(0)
	v_add_f32_e32 v44, v44, v46
	ds_bpermute_b32 v46, v62, v44
	s_waitcnt lgkmcnt(0)
	v_add_f32_e32 v44, v44, v46
	ds_bpermute_b32 v46, v63, v44
	s_waitcnt lgkmcnt(0)
	v_add_f32_e32 v44, v44, v46
	ds_bpermute_b32 v46, v65, v44
	s_waitcnt lgkmcnt(0)
	v_add_f32_e32 v44, v44, v46
	ds_bpermute_b32 v46, v67, v44
	s_waitcnt lgkmcnt(0)
	v_add_f32_e32 v44, v44, v46
	ds_bpermute_b32 v46, v68, v44
	s_waitcnt lgkmcnt(0)
; __device__ __forceinline__ unsigned pk2(float lo, float hi) { unsigned r; asm("v_cvt_pk_bf16_f32 %0, %1, %2" : "=v"(r) : "v"(lo), "v"(hi)); return r; }
; __device__ __forceinline__ float bflo(unsigned u) { return __uint_as_float(u << 16); }
; __device__ __forceinline__ float bfhi(unsigned u) { return __uint_as_float(u & 0xffff0000u); }
; template <bool FINAL>
; __device__ __forceinline__ void resid_row(const bf16_t* f, bf16_t* h, const f32x4 (&gp)[8], float alpha, float* rs_out, const f32x4 (&gn)[8], float* fin, int lane) {
;     ...
;     const float rs = rsqrtf(wave_sum(s, lane) * (1.0f / DM) + EPS) * alpha;
;     float s2 = 0.f;
; #pragma unroll
;     for (int j = 0; j < 8; ++j) { const f32x4 hv = (f32x4){bflo(wh[j].x), bfhi(wh[j].x), bflo(wh[j].y), bfhi(wh[j].y)};
;         v[j] = hv + v[j] * rs * gp[j]; s2 += (v[j].x * v[j].x + v[j].y * v[j].y) + (v[j].z * v[j].z + v[j].w * v[j].w);
;         if (!FINAL) { u32x2 hw; hw.x = pk2(v[j].x, v[j].y); hw.y = pk2(v[j].z, v[j].w); *(u32x2*)(h + 256 * j + 4 * lane) = hw; } }
;     const float rs2 = rsqrtf(wave_sum(s2, lane) * (1.0f / DM) + EPS);
;     if (!FINAL) { if (lane == 0) *rs_out = rs2; }
	v_add_f32_e32 v44, v44, v46
	v_fmamk_f32 v44, v44, 0x3a000000, v213
	v_mul_f32_e32 v46, 0x4b800000, v44
	v_cmp_gt_f32_e32 vcc, s45, v44
	s_nop 1
	v_cndmask_b32_e32 v44, v44, v46, vcc
	v_rsq_f32_e32 v44, v44
	s_nop 0
	v_mul_f32_e32 v46, 0x45800000, v44
	v_cndmask_b32_e32 v44, v44, v46, vcc
	v_mul_f32_e32 v46, v60, v44
	v_pk_mul_f32 v[74:75], v[46:47], v[78:79] op_sel_hi:[0,1]
	v_pk_mul_f32 v[76:77], v[46:47], v[80:81] op_sel_hi:[0,1]
	v_pk_fma_f32 v[56:57], v[2:3], v[76:77], v[56:57]
	v_pk_fma_f32 v[58:59], v[0:1], v[74:75], v[58:59]
	v_mov_b32_e32 v76, v82
	v_mov_b32_e32 v77, v84
	v_mov_b32_e32 v84, v83
	v_mul_f32_e32 v44, v59, v59
	v_mul_f32_e32 v69, v57, v57
	v_lshlrev_b32_e32 v74, 16, v70
	v_and_b32_e32 v75, 0xffff0000, v70
	v_lshlrev_b32_e32 v70, 16, v71
	v_and_b32_e32 v71, 0xffff0000, v71
	v_pk_mul_f32 v[76:77], v[46:47], v[76:77] op_sel_hi:[0,1]
	v_pk_mul_f32 v[78:79], v[46:47], v[84:85] op_sel_hi:[0,1]
	v_fmac_f32_e32 v44, v58, v58
	v_fmac_f32_e32 v69, v56, v56
	v_pk_fma_f32 v[70:71], v[6:7], v[78:79], v[70:71]
	v_pk_fma_f32 v[74:75], v[4:5], v[76:77], v[74:75]
	v_add_f32_e32 v44, v44, v69
	v_mul_f32_e32 v69, v75, v75
	v_mul_f32_e32 v76, v71, v71
	v_fmac_f32_e32 v69, v74, v74
	v_fmac_f32_e32 v76, v70, v70
	v_add_f32_e32 v69, v69, v76
	v_lshlrev_b32_e32 v76, 16, v72
	v_and_b32_e32 v77, 0xffff0000, v72
	v_lshlrev_b32_e32 v72, 16, v73
	v_and_b32_e32 v73, 0xffff0000, v73
	v_pk_mul_f32 v[78:79], v[46:47], v[86:87] op_sel_hi:[0,1]
	v_pk_mul_f32 v[80:81], v[46:47], v[88:89] op_sel_hi:[0,1]
	v_pk_fma_f32 v[72:73], v[10:11], v[80:81], v[72:73]
	v_pk_fma_f32 v[76:77], v[8:9], v[78:79], v[76:77]
	v_add_f32_e32 v44, v44, v69
	v_mul_f32_e32 v69, v77, v77
	v_mul_f32_e32 v78, v73, v73
	v_fmac_f32_e32 v69, v76, v76
	v_fmac_f32_e32 v78, v72, v72
	v_add_f32_e32 v69, v69, v78
	v_lshlrev_b32_e32 v78, 16, v54
	v_and_b32_e32 v79, 0xffff0000, v54
	v_lshlrev_b32_e32 v54, 16, v55
	v_and_b32_e32 v55, 0xffff0000, v55
	v_pk_mul_f32 v[80:81], v[92:93], v[46:47] op_sel_hi:[1,0]
	v_pk_mul_f32 v[82:83], v[94:95], v[46:47] op_sel_hi:[1,0]
	v_pk_fma_f32 v[78:79], v[12:13], v[80:81], v[78:79]
	v_pk_fma_f32 v[54:55], v[14:15], v[82:83], v[54:55]
	v_add_f32_e32 v44, v69, v44
	v_mul_f32_e32 v69, v79, v79
	v_mul_f32_e32 v80, v55, v55
	v_fmac_f32_e32 v69, v78, v78
	v_fmac_f32_e32 v80, v54, v54
	v_mov_b32_e32 v82, v98
	v_mov_b32_e32 v83, v100
	v_mov_b32_e32 v100, v99
	v_add_f32_e32 v69, v69, v80
	v_lshlrev_b32_e32 v80, 16, v48
	v_and_b32_e32 v81, 0xffff0000, v48
	v_lshlrev_b32_e32 v48, 16, v49
	v_and_b32_e32 v49, 0xffff0000, v49
	v_pk_mul_f32 v[82:83], v[46:47], v[82:83] op_sel_hi:[0,1]
	v_pk_mul_f32 v[84:85], v[46:47], v[100:101] op_sel_hi:[0,1]
	v_pk_fma_f32 v[48:49], v[18:19], v[84:85], v[48:49]
	v_pk_fma_f32 v[80:81], v[16:17], v[82:83], v[80:81]
	v_add_f32_e32 v44, v69, v44
	v_mul_f32_e32 v69, v81, v81
	v_mul_f32_e32 v82, v49, v49
	v_fmac_f32_e32 v69, v80, v80
	v_fmac_f32_e32 v82, v48, v48
	v_mov_b32_e32 v84, v104
	v_mov_b32_e32 v85, v106
	v_mov_b32_e32 v106, v105
	v_add_f32_e32 v69, v69, v82
	v_lshlrev_b32_e32 v82, 16, v40
	v_and_b32_e32 v83, 0xffff0000, v40
	v_lshlrev_b32_e32 v40, 16, v41
	v_and_b32_e32 v41, 0xffff0000, v41
	v_pk_mul_f32 v[84:85], v[46:47], v[84:85] op_sel_hi:[0,1]
	v_pk_mul_f32 v[86:87], v[46:47], v[106:107] op_sel_hi:[0,1]
	v_pk_fma_f32 v[40:41], v[22:23], v[86:87], v[40:41]
	v_pk_fma_f32 v[82:83], v[20:21], v[84:85], v[82:83]
	v_add_f32_e32 v44, v69, v44
	v_mul_f32_e32 v69, v83, v83
	v_mul_f32_e32 v84, v41, v41
	v_fmac_f32_e32 v69, v82, v82
	v_fmac_f32_e32 v84, v40, v40
	v_add_f32_e32 v69, v69, v84
	v_lshlrev_b32_e32 v84, 16, v38
	v_and_b32_e32 v85, 0xffff0000, v38
	v_lshlrev_b32_e32 v38, 16, v39
	v_and_b32_e32 v39, 0xffff0000, v39
	v_pk_mul_f32 v[50:51], v[46:47], v[50:51] op_sel_hi:[0,1]
	v_pk_mul_f32 v[52:53], v[46:47], v[52:53] op_sel_hi:[0,1]
	v_pk_fma_f32 v[38:39], v[26:27], v[52:53], v[38:39]
	v_pk_fma_f32 v[50:51], v[24:25], v[50:51], v[84:85]
	v_mul_f32_e32 v53, v39, v39
	v_mul_f32_e32 v52, v51, v51
	v_fmac_f32_e32 v52, v50, v50
	v_fmac_f32_e32 v53, v38, v38
	v_add_f32_e32 v44, v69, v44
	v_add_f32_e32 v52, v52, v53
	v_add_f32_e32 v69, v52, v44
	v_mov_b32_e32 v44, v47
	v_lshlrev_b32_e32 v52, 16, v36
	v_and_b32_e32 v53, 0xffff0000, v36
	v_lshlrev_b32_e32 v36, 16, v37
	v_and_b32_e32 v37, 0xffff0000, v37
	v_pk_mul_f32 v[44:45], v[44:45], v[46:47] op_sel_hi:[1,0]
	v_pk_mul_f32 v[42:43], v[42:43], v[46:47] op_sel_hi:[1,0]
	v_pk_fma_f32 v[44:45], v[28:29], v[44:45], v[52:53]
	v_pk_fma_f32 v[42:43], v[30:31], v[42:43], v[36:37]
	v_mul_f32_e32 v36, v45, v45
	v_mul_f32_e32 v37, v43, v43
	v_fmac_f32_e32 v36, v44, v44
	v_fmac_f32_e32 v37, v42, v42
	v_add_f32_e32 v36, v36, v37
	v_add_f32_e32 v46, v36, v69
	ds_bpermute_b32 v47, v61, v46
	v_cvt_pk_bf16_f32 v36, v58, v59
	v_cvt_pk_bf16_f32 v37, v56, v57
	global_store_dwordx2 v[34:35], v[36:37], off
	v_cvt_pk_bf16_f32 v36, v74, v75
	s_waitcnt lgkmcnt(0)
	v_add_f32_e32 v46, v46, v47
	ds_bpermute_b32 v47, v62, v46
	v_cvt_pk_bf16_f32 v37, v70, v71
	global_store_dwordx2 v[34:35], v[36:37], off offset:512
	v_cvt_pk_bf16_f32 v36, v76, v77
	v_cvt_pk_bf16_f32 v37, v72, v73
	s_waitcnt lgkmcnt(0)
	v_add_f32_e32 v46, v46, v47
	ds_bpermute_b32 v47, v63, v46
	global_store_dwordx2 v[34:35], v[36:37], off offset:1024
	v_cvt_pk_bf16_f32 v36, v78, v79
	v_cvt_pk_bf16_f32 v37, v54, v55
	global_store_dwordx2 v[34:35], v[36:37], off offset:1536
	s_waitcnt lgkmcnt(0)
	v_add_f32_e32 v46, v46, v47
	ds_bpermute_b32 v47, v65, v46
	v_cvt_pk_bf16_f32 v36, v80, v81
	v_cvt_pk_bf16_f32 v37, v48, v49
	global_store_dwordx2 v[34:35], v[36:37], off offset:2048
	v_cvt_pk_bf16_f32 v36, v82, v83
	s_waitcnt lgkmcnt(0)
	v_add_f32_e32 v46, v46, v47
	ds_bpermute_b32 v47, v67, v46
	v_cvt_pk_bf16_f32 v37, v40, v41
	global_store_dwordx2 v[34:35], v[36:37], off offset:2560
	v_cvt_pk_bf16_f32 v40, v50, v51
	v_cvt_pk_bf16_f32 v41, v38, v39
	s_waitcnt lgkmcnt(0)
	v_add_f32_e32 v36, v46, v47
	ds_bpermute_b32 v37, v68, v36
	global_store_dwordx2 v[34:35], v[40:41], off offset:3072
	v_cvt_pk_bf16_f32 v38, v44, v45
	v_cvt_pk_bf16_f32 v39, v42, v43
	global_store_dwordx2 v[34:35], v[38:39], off offset:3584
	s_and_saveexec_b64 s[8:9], s[38:39]
	s_cbranch_execz .LBB0_245
	s_waitcnt lgkmcnt(0)
	v_add_f32_e32 v34, v36, v37
	v_fmamk_f32 v34, v34, 0x3a000000, v213
	v_mul_f32_e32 v35, 0x4b800000, v34
	v_cmp_gt_f32_e32 vcc, s45, v34
	s_add_u32 s12, s66, s6
	s_addc_u32 s13, s67, s7
	v_cndmask_b32_e32 v34, v34, v35, vcc
	v_rsq_f32_e32 v34, v34
	s_nop 0
	v_mul_f32_e32 v35, 0x45800000, v34
	v_cndmask_b32_e32 v34, v34, v35, vcc
	global_store_dword v145, v34, s[12:13]
	s_branch .LBB0_245

; #define LAS __attribute__((address_space(3)))
; #define SCHED_FENCE() __builtin_amdgcn_sched_barrier(0)
; __device__ __forceinline__ void transpose_item(const float* W, int K, int N, bf16_t* WT, int kb, int nbd, int src0, LAS float* scr, int lane, const float* gk = nullptr) {
;     const int k0 = kb * 64;
;     const float* wp = W + (size_t)(k0 + (lane >> 4)) * N + src0 + (lane & 15) * 4;
;     f32x4 v[16];
; #pragma unroll
;     for (int i = 0; i < 16; ++i) v[i] = *(const f32x4*)(wp + (size_t)(4 * i) * N);
;     SCHED_FENCE();
; #pragma unroll
;     for (int i = 0; i < 16; ++i) { if (gk) v[i] = v[i] * gk[k0 + 4 * i + (lane >> 4)];
;         LAS float* s = scr + (4 * i + (lane >> 4)) * 65 + (lane & 15) * 4; s[0] = v[i].x; s[1] = v[i].y; s[2] = v[i].z; s[3] = v[i].w; }
.LBB0_278:
	s_lshl_b32 s8, s7, 6
	v_readlane_b32 s80, v252, 0
	s_and_b32 s7, s8, 0xffc0
	v_readlane_b32 s84, v252, 4
	v_readlane_b32 s85, v252, 5
	v_or_b32_e32 v64, s7, v92
	s_movk_i32 s7, 0x4800
	v_mov_b64_e32 v[0:1], s[84:85]
	v_mad_u64_u32 v[0:1], s[30:31], v64, s7, v[0:1]
	s_ashr_i32 s7, s6, 31
	v_lshl_add_u64 v[0:1], s[6:7], 2, v[0:1]
	v_lshlrev_b32_e32 v144, 2, v70
	v_lshl_add_u64 v[0:1], v[0:1], 0, v[144:145]
	v_add_co_u32_e32 v2, vcc, 0x12000, v0
	s_mov_b32 s0, 0x90000
	s_nop 0
	v_addc_co_u32_e32 v3, vcc, 0, v1, vcc
	global_load_dwordx4 v[56:59], v[0:1], off nt
	global_load_dwordx4 v[60:63], v[2:3], off nt
	v_add_co_u32_e32 v2, vcc, 0x24000, v0
	v_readlane_b32 s81, v252, 1
	s_nop 0
	v_addc_co_u32_e32 v3, vcc, 0, v1, vcc
	v_add_co_u32_e32 v4, vcc, 0x36000, v0
	v_readlane_b32 s82, v252, 2
	s_waitcnt lgkmcnt(0)
	v_addc_co_u32_e32 v5, vcc, 0, v1, vcc
	global_load_dwordx4 v[48:51], v[2:3], off nt
	global_load_dwordx4 v[52:55], v[4:5], off nt
	v_add_co_u32_e32 v2, vcc, 0x48000, v0
	v_readlane_b32 s83, v252, 3
	s_nop 0
	v_addc_co_u32_e32 v3, vcc, 0, v1, vcc
	v_add_co_u32_e32 v4, vcc, 0x5a000, v0
	v_readlane_b32 s86, v252, 6
	s_nop 0
	v_addc_co_u32_e32 v5, vcc, 0, v1, vcc
	global_load_dwordx4 v[40:43], v[2:3], off nt
	global_load_dwordx4 v[44:47], v[4:5], off nt
	v_add_co_u32_e32 v2, vcc, 0x6c000, v0
	v_readlane_b32 s87, v252, 7
	s_nop 0
	v_addc_co_u32_e32 v3, vcc, 0, v1, vcc
	v_add_co_u32_e32 v4, vcc, 0x7e000, v0
	v_readlane_b32 s88, v252, 8
	s_nop 0
	v_addc_co_u32_e32 v5, vcc, 0, v1, vcc
	global_load_dwordx4 v[32:35], v[2:3], off nt
	s_waitcnt lgkmcnt(0)
	global_load_dwordx4 v[36:39], v[4:5], off nt
	v_add_co_u32_e32 v2, vcc, s0, v0
	v_readlane_b32 s89, v252, 9
	s_nop 0
	v_addc_co_u32_e32 v3, vcc, 0, v1, vcc
	v_add_co_u32_e32 v4, vcc, 0xa2000, v0
	v_readlane_b32 s90, v252, 10
	s_nop 0
	v_addc_co_u32_e32 v5, vcc, 0, v1, vcc
	global_load_dwordx4 v[24:27], v[2:3], off nt
	global_load_dwordx4 v[28:31], v[4:5], off nt
	v_add_co_u32_e32 v2, vcc, 0xb4000, v0
	v_readlane_b32 s91, v252, 11
	s_nop 0
	v_addc_co_u32_e32 v3, vcc, 0, v1, vcc
	v_add_co_u32_e32 v4, vcc, 0xc6000, v0
	v_readlane_b32 s92, v252, 12
	s_nop 0
	v_addc_co_u32_e32 v5, vcc, 0, v1, vcc
	global_load_dwordx4 v[16:19], v[2:3], off nt
	global_load_dwordx4 v[20:23], v[4:5], off nt
	v_add_co_u32_e32 v2, vcc, 0xd8000, v0
	v_readlane_b32 s93, v252, 13
	s_nop 0
	v_addc_co_u32_e32 v3, vcc, 0, v1, vcc
	v_add_co_u32_e32 v4, vcc, 0xea000, v0
	v_readlane_b32 s94, v252, 14
	s_nop 0
	v_addc_co_u32_e32 v5, vcc, 0, v1, vcc
	global_load_dwordx4 v[8:11], v[2:3], off nt
	global_load_dwordx4 v[12:15], v[4:5], off nt
	v_add_co_u32_e32 v2, vcc, 0xfc000, v0
	v_readlane_b32 s95, v252, 15
	s_nop 0
	v_addc_co_u32_e32 v3, vcc, 0, v1, vcc
	v_add_co_u32_e32 v4, vcc, 0x10e000, v0
	s_nop 1
	v_addc_co_u32_e32 v5, vcc, 0, v1, vcc
	global_load_dwordx4 v[0:3], v[2:3], off nt
	s_nop 0
	global_load_dwordx4 v[4:7], v[4:5], off nt
	v_readlane_b32 s0, v251, 20
	v_readlane_b32 s1, v251, 21
	s_andn2_b64 vcc, exec, s[0:1]
	v_lshlrev_b32_e32 v90, 2, v64
	v_cndmask_b32_e64 v65, 0, 1, s[0:1]
	v_cmp_ne_u32_e64 s[38:39], 1, v65
	s_cbranch_vccnz .LBB0_378
	global_load_dword v160, v90, s[80:81]
	global_load_dword v161, v90, s[80:81] offset:16
	global_load_dword v162, v90, s[80:81] offset:32
	global_load_dword v163, v90, s[80:81] offset:48
	global_load_dword v164, v90, s[80:81] offset:64
	global_load_dword v165, v90, s[80:81] offset:80
	global_load_dword v166, v90, s[80:81] offset:96
	global_load_dword v167, v90, s[80:81] offset:112
	global_load_dword v168, v90, s[80:81] offset:128
	global_load_dword v169, v90, s[80:81] offset:144
	global_load_dword v170, v90, s[80:81] offset:160
	global_load_dword v171, v90, s[80:81] offset:176
	global_load_dword v172, v90, s[80:81] offset:192
	global_load_dword v173, v90, s[80:81] offset:208
	global_load_dword v174, v90, s[80:81] offset:224
	global_load_dword v175, v90, s[80:81] offset:240
	s_waitcnt vmcnt(0)
	v_mov_b32_e32 v64, v160
	v_mov_b32_e32 v104, v161
	s_waitcnt vmcnt(1)
	v_pk_mul_f32 v[86:87], v[58:59], v[64:65] op_sel_hi:[1,0]
	v_pk_mul_f32 v[88:89], v[56:57], v[64:65] op_sel_hi:[1,0]
	s_waitcnt vmcnt(0)
	v_pk_mul_f32 v[66:67], v[62:63], v[104:105] op_sel_hi:[1,0]
	v_pk_mul_f32 v[64:65], v[60:61], v[104:105] op_sel_hi:[1,0]
	s_cbranch_execnz .LBB0_281

; #define LAS __attribute__((address_space(3)))
; __device__ __forceinline__ void transpose_item(const float* W, int K, int N, bf16_t* WT, int kb, int nbd, int src0, LAS float* scr, int lane, const float* gk = nullptr) {
;     ...
;     for (int i = 0; i < 16; ++i) { if (gk) v[i] = v[i] * gk[k0 + 4 * i + (lane >> 4)];
;         LAS float* s = scr + (4 * i + (lane >> 4)) * 65 + (lane & 15) * 4; s[0] = v[i].x; s[1] = v[i].y; s[2] = v[i].z; s[3] = v[i].w; }
.LBB0_281:
	s_waitcnt vmcnt(15)
	v_add_u32_e32 v56, 0x410, v93
	ds_write2_b32 v93, v88, v89 offset1:1
	ds_write2_b32 v93, v86, v87 offset0:2 offset1:3
	ds_write2_b32 v56, v64, v65 offset1:1
	v_add_u32_e32 v56, 0x418, v93
	s_and_b64 vcc, exec, s[38:39]
	ds_write2_b32 v56, v66, v67 offset1:1
	s_cbranch_vccnz .LBB0_379
	v_readlane_b32 s80, v252, 0
	v_readlane_b32 s81, v252, 1
	s_nop 4
	v_mov_b32_e32 v56, v162
	v_mov_b32_e32 v64, v163
	v_readlane_b32 s82, v252, 2
	v_readlane_b32 s83, v252, 3
	v_readlane_b32 s84, v252, 4
	v_readlane_b32 s85, v252, 5
	v_readlane_b32 s86, v252, 6
	v_readlane_b32 s87, v252, 7
	v_readlane_b32 s88, v252, 8
	v_readlane_b32 s89, v252, 9
	v_readlane_b32 s90, v252, 10
	v_readlane_b32 s91, v252, 11
	v_readlane_b32 s92, v252, 12
	v_readlane_b32 s93, v252, 13
	v_readlane_b32 s94, v252, 14
	v_readlane_b32 s95, v252, 15
	s_waitcnt vmcnt(1)
	v_pk_mul_f32 v[60:61], v[50:51], v[56:57] op_sel_hi:[1,0]
	v_pk_mul_f32 v[62:63], v[48:49], v[56:57] op_sel_hi:[1,0]
	s_waitcnt vmcnt(0)
	v_pk_mul_f32 v[58:59], v[54:55], v[64:65] op_sel_hi:[1,0]
	v_pk_mul_f32 v[56:57], v[52:53], v[64:65] op_sel_hi:[1,0]
	s_cbranch_execnz .LBB0_284

; #define LAS __attribute__((address_space(3)))
; __device__ __forceinline__ void transpose_item(const float* W, int K, int N, bf16_t* WT, int kb, int nbd, int src0, LAS float* scr, int lane, const float* gk = nullptr) {
;     ...
;     for (int i = 0; i < 16; ++i) { if (gk) v[i] = v[i] * gk[k0 + 4 * i + (lane >> 4)];
;         LAS float* s = scr + (4 * i + (lane >> 4)) * 65 + (lane & 15) * 4; s[0] = v[i].x; s[1] = v[i].y; s[2] = v[i].z; s[3] = v[i].w; }
.LBB0_284:
	s_waitcnt vmcnt(13)
	v_add_u32_e32 v48, 0x820, v93
	ds_write2_b32 v48, v62, v63 offset1:1
	v_add_u32_e32 v48, 0x828, v93
	ds_write2_b32 v48, v60, v61 offset1:1
	v_add_u32_e32 v48, 0xc30, v93
	ds_write2_b32 v48, v56, v57 offset1:1
	v_add_u32_e32 v48, 0xc38, v93
	s_and_b64 vcc, exec, s[38:39]
	ds_write2_b32 v48, v58, v59 offset1:1
	s_cbranch_vccnz .LBB0_380
	v_readlane_b32 s80, v252, 0
	v_readlane_b32 s81, v252, 1
	s_nop 4
	v_mov_b32_e32 v48, v164
	v_mov_b32_e32 v56, v165
	v_readlane_b32 s82, v252, 2
	v_readlane_b32 s83, v252, 3
	v_readlane_b32 s84, v252, 4
	v_readlane_b32 s85, v252, 5
	v_readlane_b32 s86, v252, 6
	v_readlane_b32 s87, v252, 7
	v_readlane_b32 s88, v252, 8
	v_readlane_b32 s89, v252, 9
	v_readlane_b32 s90, v252, 10
	v_readlane_b32 s91, v252, 11
	v_readlane_b32 s92, v252, 12
	v_readlane_b32 s93, v252, 13
	v_readlane_b32 s94, v252, 14
	v_readlane_b32 s95, v252, 15
	s_waitcnt vmcnt(1)
	v_pk_mul_f32 v[52:53], v[42:43], v[48:49] op_sel_hi:[1,0]
	v_pk_mul_f32 v[54:55], v[40:41], v[48:49] op_sel_hi:[1,0]
	s_waitcnt vmcnt(0)
	v_pk_mul_f32 v[50:51], v[46:47], v[56:57] op_sel_hi:[1,0]
	v_pk_mul_f32 v[48:49], v[44:45], v[56:57] op_sel_hi:[1,0]
	s_cbranch_execnz .LBB0_287

; #define LAS __attribute__((address_space(3)))
; __device__ __forceinline__ void transpose_item(const float* W, int K, int N, bf16_t* WT, int kb, int nbd, int src0, LAS float* scr, int lane, const float* gk = nullptr) {
;     ...
;     for (int i = 0; i < 16; ++i) { if (gk) v[i] = v[i] * gk[k0 + 4 * i + (lane >> 4)];
;         LAS float* s = scr + (4 * i + (lane >> 4)) * 65 + (lane & 15) * 4; s[0] = v[i].x; s[1] = v[i].y; s[2] = v[i].z; s[3] = v[i].w; }
.LBB0_287:
	s_waitcnt vmcnt(11)
	v_add_u32_e32 v40, 0x1040, v93
	ds_write2_b32 v40, v54, v55 offset1:1
	v_add_u32_e32 v40, 0x1048, v93
	ds_write2_b32 v40, v52, v53 offset1:1
	v_add_u32_e32 v40, 0x1450, v93
	ds_write2_b32 v40, v48, v49 offset1:1
	v_add_u32_e32 v40, 0x1458, v93
	s_and_b64 vcc, exec, s[38:39]
	ds_write2_b32 v40, v50, v51 offset1:1
	s_cbranch_vccnz .LBB0_381
	v_readlane_b32 s80, v252, 0
	v_readlane_b32 s81, v252, 1
	s_nop 4
	v_mov_b32_e32 v40, v166
	v_mov_b32_e32 v48, v167
	v_readlane_b32 s82, v252, 2
	v_readlane_b32 s83, v252, 3
	v_readlane_b32 s84, v252, 4
	v_readlane_b32 s85, v252, 5
	v_readlane_b32 s86, v252, 6
	v_readlane_b32 s87, v252, 7
	v_readlane_b32 s88, v252, 8
	v_readlane_b32 s89, v252, 9
	v_readlane_b32 s90, v252, 10
	v_readlane_b32 s91, v252, 11
	v_readlane_b32 s92, v252, 12
	v_readlane_b32 s93, v252, 13
	v_readlane_b32 s94, v252, 14
	v_readlane_b32 s95, v252, 15
	s_waitcnt vmcnt(1)
	v_pk_mul_f32 v[44:45], v[34:35], v[40:41] op_sel_hi:[1,0]
	v_pk_mul_f32 v[46:47], v[32:33], v[40:41] op_sel_hi:[1,0]
	s_waitcnt vmcnt(0)
	v_pk_mul_f32 v[42:43], v[38:39], v[48:49] op_sel_hi:[1,0]
	v_pk_mul_f32 v[40:41], v[36:37], v[48:49] op_sel_hi:[1,0]
	s_cbranch_execnz .LBB0_290

; #define LAS __attribute__((address_space(3)))
; __device__ __forceinline__ void transpose_item(const float* W, int K, int N, bf16_t* WT, int kb, int nbd, int src0, LAS float* scr, int lane, const float* gk = nullptr) {
;     ...
;     for (int i = 0; i < 16; ++i) { if (gk) v[i] = v[i] * gk[k0 + 4 * i + (lane >> 4)];
;         LAS float* s = scr + (4 * i + (lane >> 4)) * 65 + (lane & 15) * 4; s[0] = v[i].x; s[1] = v[i].y; s[2] = v[i].z; s[3] = v[i].w; }
.LBB0_290:
	s_waitcnt vmcnt(9)
	v_add_u32_e32 v32, 0x1860, v93
	ds_write2_b32 v32, v46, v47 offset1:1
	v_add_u32_e32 v32, 0x1868, v93
	ds_write2_b32 v32, v44, v45 offset1:1
	v_add_u32_e32 v32, 0x1c70, v93
	ds_write2_b32 v32, v40, v41 offset1:1
	v_add_u32_e32 v32, 0x1c78, v93
	s_and_b64 vcc, exec, s[38:39]
	ds_write2_b32 v32, v42, v43 offset1:1
	s_cbranch_vccnz .LBB0_382
	v_readlane_b32 s80, v252, 0
	v_readlane_b32 s81, v252, 1
	s_nop 4
	v_mov_b32_e32 v32, v168
	v_mov_b32_e32 v40, v169
	v_readlane_b32 s82, v252, 2
	v_readlane_b32 s83, v252, 3
	v_readlane_b32 s84, v252, 4
	v_readlane_b32 s85, v252, 5
	v_readlane_b32 s86, v252, 6
	v_readlane_b32 s87, v252, 7
	v_readlane_b32 s88, v252, 8
	v_readlane_b32 s89, v252, 9
	v_readlane_b32 s90, v252, 10
	v_readlane_b32 s91, v252, 11
	v_readlane_b32 s92, v252, 12
	v_readlane_b32 s93, v252, 13
	v_readlane_b32 s94, v252, 14
	v_readlane_b32 s95, v252, 15
	s_waitcnt vmcnt(1)
	v_pk_mul_f32 v[36:37], v[26:27], v[32:33] op_sel_hi:[1,0]
	v_pk_mul_f32 v[38:39], v[24:25], v[32:33] op_sel_hi:[1,0]
	s_waitcnt vmcnt(0)
	v_pk_mul_f32 v[34:35], v[30:31], v[40:41] op_sel_hi:[1,0]
	v_pk_mul_f32 v[32:33], v[28:29], v[40:41] op_sel_hi:[1,0]
	s_cbranch_execnz .LBB0_293

; #define LAS __attribute__((address_space(3)))
; __device__ __forceinline__ void transpose_item(const float* W, int K, int N, bf16_t* WT, int kb, int nbd, int src0, LAS float* scr, int lane, const float* gk = nullptr) {
;     ...
;     for (int i = 0; i < 16; ++i) { if (gk) v[i] = v[i] * gk[k0 + 4 * i + (lane >> 4)];
;         LAS float* s = scr + (4 * i + (lane >> 4)) * 65 + (lane & 15) * 4; s[0] = v[i].x; s[1] = v[i].y; s[2] = v[i].z; s[3] = v[i].w; }
.LBB0_293:
	s_waitcnt vmcnt(7)
	v_add_u32_e32 v24, 0x2080, v93
	ds_write2_b32 v24, v38, v39 offset1:1
	v_add_u32_e32 v24, 0x2088, v93
	ds_write2_b32 v24, v36, v37 offset1:1
	v_add_u32_e32 v24, 0x2490, v93
	ds_write2_b32 v24, v32, v33 offset1:1
	v_add_u32_e32 v24, 0x2498, v93
	s_and_b64 vcc, exec, s[38:39]
	ds_write2_b32 v24, v34, v35 offset1:1
	s_cbranch_vccnz .LBB0_383
	v_readlane_b32 s80, v252, 0
	v_readlane_b32 s81, v252, 1
	s_nop 4
	v_mov_b32_e32 v24, v170
	v_mov_b32_e32 v32, v171
	v_readlane_b32 s82, v252, 2
	v_readlane_b32 s83, v252, 3
	v_readlane_b32 s84, v252, 4
	v_readlane_b32 s85, v252, 5
	v_readlane_b32 s86, v252, 6
	v_readlane_b32 s87, v252, 7
	v_readlane_b32 s88, v252, 8
	v_readlane_b32 s89, v252, 9
	v_readlane_b32 s90, v252, 10
	v_readlane_b32 s91, v252, 11
	v_readlane_b32 s92, v252, 12
	v_readlane_b32 s93, v252, 13
	v_readlane_b32 s94, v252, 14
	v_readlane_b32 s95, v252, 15
	s_waitcnt vmcnt(1)
	v_pk_mul_f32 v[28:29], v[18:19], v[24:25] op_sel_hi:[1,0]
	v_pk_mul_f32 v[30:31], v[16:17], v[24:25] op_sel_hi:[1,0]
	s_waitcnt vmcnt(0)
	v_pk_mul_f32 v[26:27], v[22:23], v[32:33] op_sel_hi:[1,0]
	v_pk_mul_f32 v[24:25], v[20:21], v[32:33] op_sel_hi:[1,0]
	s_cbranch_execnz .LBB0_296

; #define LAS __attribute__((address_space(3)))
; __device__ __forceinline__ void transpose_item(const float* W, int K, int N, bf16_t* WT, int kb, int nbd, int src0, LAS float* scr, int lane, const float* gk = nullptr) {
;     ...
;     for (int i = 0; i < 16; ++i) { if (gk) v[i] = v[i] * gk[k0 + 4 * i + (lane >> 4)];
;         LAS float* s = scr + (4 * i + (lane >> 4)) * 65 + (lane & 15) * 4; s[0] = v[i].x; s[1] = v[i].y; s[2] = v[i].z; s[3] = v[i].w; }
.LBB0_296:
	s_waitcnt vmcnt(5)
	v_add_u32_e32 v16, 0x28a0, v93
	ds_write2_b32 v16, v30, v31 offset1:1
	v_add_u32_e32 v16, 0x28a8, v93
	ds_write2_b32 v16, v28, v29 offset1:1
	v_add_u32_e32 v16, 0x2cb0, v93
	ds_write2_b32 v16, v24, v25 offset1:1
	v_add_u32_e32 v16, 0x2cb8, v93
	s_and_b64 vcc, exec, s[38:39]
	ds_write2_b32 v16, v26, v27 offset1:1
	s_cbranch_vccnz .LBB0_384
	v_readlane_b32 s80, v252, 0
	v_readlane_b32 s81, v252, 1
	s_nop 4
	v_mov_b32_e32 v16, v172
	v_mov_b32_e32 v24, v173
	v_readlane_b32 s82, v252, 2
	v_readlane_b32 s83, v252, 3
	v_readlane_b32 s84, v252, 4
	v_readlane_b32 s85, v252, 5
	v_readlane_b32 s86, v252, 6
	v_readlane_b32 s87, v252, 7
	v_readlane_b32 s88, v252, 8
	v_readlane_b32 s89, v252, 9
	v_readlane_b32 s90, v252, 10
	v_readlane_b32 s91, v252, 11
	v_readlane_b32 s92, v252, 12
	v_readlane_b32 s93, v252, 13
	v_readlane_b32 s94, v252, 14
	v_readlane_b32 s95, v252, 15
	s_waitcnt vmcnt(1)
	v_pk_mul_f32 v[20:21], v[10:11], v[16:17] op_sel_hi:[1,0]
	v_pk_mul_f32 v[22:23], v[8:9], v[16:17] op_sel_hi:[1,0]
	s_waitcnt vmcnt(0)
	v_pk_mul_f32 v[18:19], v[14:15], v[24:25] op_sel_hi:[1,0]
	v_pk_mul_f32 v[16:17], v[12:13], v[24:25] op_sel_hi:[1,0]
	s_cbranch_execnz .LBB0_299

; #define LAS __attribute__((address_space(3)))
; __device__ __forceinline__ void transpose_item(const float* W, int K, int N, bf16_t* WT, int kb, int nbd, int src0, LAS float* scr, int lane, const float* gk = nullptr) {
;     ...
;     for (int i = 0; i < 16; ++i) { if (gk) v[i] = v[i] * gk[k0 + 4 * i + (lane >> 4)];
;         LAS float* s = scr + (4 * i + (lane >> 4)) * 65 + (lane & 15) * 4; s[0] = v[i].x; s[1] = v[i].y; s[2] = v[i].z; s[3] = v[i].w; }
.LBB0_299:
	s_waitcnt vmcnt(3)
	v_add_u32_e32 v8, 0x30c0, v93
	ds_write2_b32 v8, v22, v23 offset1:1
	v_add_u32_e32 v8, 0x30c8, v93
	ds_write2_b32 v8, v20, v21 offset1:1
	v_add_u32_e32 v8, 0x34d0, v93
	ds_write2_b32 v8, v16, v17 offset1:1
	v_add_u32_e32 v8, 0x34d8, v93
	s_and_b64 vcc, exec, s[38:39]
	ds_write2_b32 v8, v18, v19 offset1:1
	s_cbranch_vccnz .LBB0_385
	v_readlane_b32 s80, v252, 0
	v_readlane_b32 s81, v252, 1
	s_nop 4
	v_mov_b32_e32 v8, v174
	v_mov_b32_e32 v16, v175
	v_readlane_b32 s82, v252, 2
	v_readlane_b32 s83, v252, 3
	v_readlane_b32 s84, v252, 4
	v_readlane_b32 s85, v252, 5
	v_readlane_b32 s86, v252, 6
	v_readlane_b32 s87, v252, 7
	v_readlane_b32 s88, v252, 8
	v_readlane_b32 s89, v252, 9
	v_readlane_b32 s90, v252, 10
	v_readlane_b32 s91, v252, 11
	v_readlane_b32 s92, v252, 12
	v_readlane_b32 s93, v252, 13
	v_readlane_b32 s94, v252, 14
	v_readlane_b32 s95, v252, 15
	s_waitcnt vmcnt(1)
	v_pk_mul_f32 v[12:13], v[2:3], v[8:9] op_sel_hi:[1,0]
	v_pk_mul_f32 v[14:15], v[0:1], v[8:9] op_sel_hi:[1,0]
	s_waitcnt vmcnt(0)
	v_pk_mul_f32 v[10:11], v[6:7], v[16:17] op_sel_hi:[1,0]
	v_pk_mul_f32 v[8:9], v[4:5], v[16:17] op_sel_hi:[1,0]
	s_cbranch_execnz .LBB0_302

; #define LAS __attribute__((address_space(3)))
; #define SCHED_FENCE() __builtin_amdgcn_sched_barrier(0)
; __device__ __forceinline__ void transpose_item(const float* W, int K, int N, bf16_t* WT, int kb, int nbd, int src0, LAS float* scr, int lane, const float* gk = nullptr) {
;     const int k0 = kb * 64;
;     const float* wp = W + (size_t)(k0 + (lane >> 4)) * N + src0 + (lane & 15) * 4;
;     f32x4 v[16];
; #pragma unroll
;     for (int i = 0; i < 16; ++i) v[i] = *(const f32x4*)(wp + (size_t)(4 * i) * N);
;     SCHED_FENCE();
; #pragma unroll
;     for (int i = 0; i < 16; ++i) { if (gk) v[i] = v[i] * gk[k0 + 4 * i + (lane >> 4)];
;         LAS float* s = scr + (4 * i + (lane >> 4)) * 65 + (lane & 15) * 4; s[0] = v[i].x; s[1] = v[i].y; s[2] = v[i].z; s[3] = v[i].w; }
.LBB0_310:
	s_andn2_b64 vcc, exec, s[6:7]
	s_cbranch_vccnz .LBB0_336
	s_add_i32 s6, s28, 0xea00
	s_and_b32 s7, s6, 0xffff
	s_mul_i32 s7, s7, 0xba2f
	s_lshr_b32 s7, s7, 23
	s_mul_i32 s8, s7, 0xb0
	s_sub_i32 s6, s6, s8
	s_and_b32 s8, s6, 0xffff
	s_and_b32 s6, s6, 3
	s_lshl_b32 s9, s8, 5
	s_and_b32 s9, s9, 0x1f80
	s_lshl_b32 s29, s6, 6
	s_or_b32 s30, s9, s29
	s_add_i32 s9, s29, s9
	s_addk_i32 s9, 0x1580
	s_cmp_lt_u32 s6, 2
	s_cselect_b32 s29, s30, s9
	s_lshl_b32 s9, s7, 6
	v_or_b32_e32 v64, s9, v92
	v_mov_b64_e32 v[0:1], s[78:79]
	s_mov_b32 s0, 0xb000
	v_mad_u64_u32 v[0:1], s[6:7], v64, s0, v[0:1]
	s_lshl_b32 s74, s29, 2
	v_lshl_add_u64 v[0:1], v[0:1], 0, s[74:75]
	v_lshlrev_b32_e32 v144, 2, v70
	v_lshl_add_u64 v[0:1], v[0:1], 0, v[144:145]
	s_mov_b32 s0, 0x2c000
	v_add_co_u32_e32 v2, vcc, s0, v0
	s_mov_b32 s0, 0x58000
	s_nop 0
	v_addc_co_u32_e32 v3, vcc, 0, v1, vcc
	global_load_dwordx4 v[56:59], v[0:1], off nt
	global_load_dwordx4 v[60:63], v[2:3], off nt
	v_add_co_u32_e32 v2, vcc, s0, v0
	s_mov_b32 s0, 0x84000
	s_nop 0
	v_addc_co_u32_e32 v3, vcc, 0, v1, vcc
	v_add_co_u32_e32 v4, vcc, s0, v0
	s_mov_b32 s0, 0xb0000
	s_waitcnt lgkmcnt(0)
	v_addc_co_u32_e32 v5, vcc, 0, v1, vcc
	global_load_dwordx4 v[48:51], v[2:3], off nt
	global_load_dwordx4 v[52:55], v[4:5], off nt
	v_add_co_u32_e32 v2, vcc, s0, v0
	s_mov_b32 s0, 0xdc000
	s_nop 0
	v_addc_co_u32_e32 v3, vcc, 0, v1, vcc
	v_add_co_u32_e32 v4, vcc, s0, v0
	s_mov_b32 s0, 0x108000
	s_nop 0
	v_addc_co_u32_e32 v5, vcc, 0, v1, vcc
	global_load_dwordx4 v[40:43], v[2:3], off nt
	global_load_dwordx4 v[44:47], v[4:5], off nt
	v_add_co_u32_e32 v2, vcc, s0, v0
	s_mov_b32 s0, 0x134000
	s_nop 0
	v_addc_co_u32_e32 v3, vcc, 0, v1, vcc
	v_add_co_u32_e32 v4, vcc, s0, v0
	s_mov_b32 s0, 0x160000
	s_nop 0
	v_addc_co_u32_e32 v5, vcc, 0, v1, vcc
	global_load_dwordx4 v[32:35], v[2:3], off nt
	s_waitcnt lgkmcnt(0)
	global_load_dwordx4 v[36:39], v[4:5], off nt
	v_add_co_u32_e32 v2, vcc, s0, v0
	s_mov_b32 s0, 0x18c000
	s_nop 0
	v_addc_co_u32_e32 v3, vcc, 0, v1, vcc
	v_add_co_u32_e32 v4, vcc, s0, v0
	s_mov_b32 s0, 0x1b8000
	s_nop 0
	v_addc_co_u32_e32 v5, vcc, 0, v1, vcc
	global_load_dwordx4 v[24:27], v[2:3], off nt
	global_load_dwordx4 v[28:31], v[4:5], off nt
	v_add_co_u32_e32 v2, vcc, s0, v0
	s_mov_b32 s0, 0x1e4000
	s_nop 0
	v_addc_co_u32_e32 v3, vcc, 0, v1, vcc
	v_add_co_u32_e32 v4, vcc, s0, v0
	s_mov_b32 s0, 0x210000
	s_nop 0
	v_addc_co_u32_e32 v5, vcc, 0, v1, vcc
	global_load_dwordx4 v[16:19], v[2:3], off nt
	global_load_dwordx4 v[20:23], v[4:5], off nt
	v_add_co_u32_e32 v2, vcc, s0, v0
	s_nop 1
	v_addc_co_u32_e32 v3, vcc, 0, v1, vcc
	v_add_co_u32_e32 v4, vcc, 0x23c000, v0
	s_nop 1
	v_addc_co_u32_e32 v5, vcc, 0, v1, vcc
	global_load_dwordx4 v[8:11], v[2:3], off nt
	global_load_dwordx4 v[12:15], v[4:5], off nt
	v_add_co_u32_e32 v2, vcc, 0x268000, v0
	s_nop 1
	v_addc_co_u32_e32 v3, vcc, 0, v1, vcc
	v_add_co_u32_e32 v4, vcc, 0x294000, v0
	s_nop 1
	v_addc_co_u32_e32 v5, vcc, 0, v1, vcc
	global_load_dwordx4 v[0:3], v[2:3], off nt
	s_nop 0
	global_load_dwordx4 v[4:7], v[4:5], off nt
	v_readlane_b32 s0, v251, 22
	v_readlane_b32 s1, v251, 23
	s_andn2_b64 vcc, exec, s[0:1]
	v_lshlrev_b32_e32 v90, 2, v64
	v_cndmask_b32_e64 v65, 0, 1, s[0:1]
	v_cmp_ne_u32_e64 s[38:39], 1, v65
	s_cbranch_vccnz .LBB0_370
	global_load_dword v160, v90, s[76:77]
	global_load_dword v161, v90, s[76:77] offset:16
	global_load_dword v162, v90, s[76:77] offset:32
	global_load_dword v163, v90, s[76:77] offset:48
	global_load_dword v164, v90, s[76:77] offset:64
	global_load_dword v165, v90, s[76:77] offset:80
	global_load_dword v166, v90, s[76:77] offset:96
	global_load_dword v167, v90, s[76:77] offset:112
	global_load_dword v168, v90, s[76:77] offset:128
	global_load_dword v169, v90, s[76:77] offset:144
	global_load_dword v170, v90, s[76:77] offset:160
	global_load_dword v171, v90, s[76:77] offset:176
	global_load_dword v172, v90, s[76:77] offset:192
	global_load_dword v173, v90, s[76:77] offset:208
	global_load_dword v174, v90, s[76:77] offset:224
	global_load_dword v175, v90, s[76:77] offset:240
	s_waitcnt vmcnt(0)
	v_mov_b32_e32 v64, v160
	v_mov_b32_e32 v104, v161
	s_waitcnt vmcnt(1)
	v_pk_mul_f32 v[86:87], v[58:59], v[64:65] op_sel_hi:[1,0]
	v_pk_mul_f32 v[88:89], v[56:57], v[64:65] op_sel_hi:[1,0]
	s_waitcnt vmcnt(0)
	v_pk_mul_f32 v[66:67], v[62:63], v[104:105] op_sel_hi:[1,0]
	v_pk_mul_f32 v[64:65], v[60:61], v[104:105] op_sel_hi:[1,0]
	s_cbranch_execnz .LBB0_314

; #define LAS __attribute__((address_space(3)))
; __device__ __forceinline__ void transpose_item(const float* W, int K, int N, bf16_t* WT, int kb, int nbd, int src0, LAS float* scr, int lane, const float* gk = nullptr) {
;     ...
;     for (int i = 0; i < 16; ++i) { if (gk) v[i] = v[i] * gk[k0 + 4 * i + (lane >> 4)];
;         LAS float* s = scr + (4 * i + (lane >> 4)) * 65 + (lane & 15) * 4; s[0] = v[i].x; s[1] = v[i].y; s[2] = v[i].z; s[3] = v[i].w; }
.LBB0_314:
	s_waitcnt vmcnt(15)
	v_add_u32_e32 v56, 0x410, v93
	ds_write2_b32 v93, v88, v89 offset1:1
	ds_write2_b32 v93, v86, v87 offset0:2 offset1:3
	ds_write2_b32 v56, v64, v65 offset1:1
	v_add_u32_e32 v56, 0x418, v93
	s_and_b64 vcc, exec, s[38:39]
	ds_write2_b32 v56, v66, v67 offset1:1
	s_cbranch_vccnz .LBB0_371
	v_mov_b32_e32 v56, v162
	v_mov_b32_e32 v64, v163
	s_waitcnt vmcnt(1)
	v_pk_mul_f32 v[60:61], v[50:51], v[56:57] op_sel_hi:[1,0]
	v_pk_mul_f32 v[62:63], v[48:49], v[56:57] op_sel_hi:[1,0]
	s_waitcnt vmcnt(0)
	v_pk_mul_f32 v[58:59], v[54:55], v[64:65] op_sel_hi:[1,0]
	v_pk_mul_f32 v[56:57], v[52:53], v[64:65] op_sel_hi:[1,0]
	s_cbranch_execnz .LBB0_317

; #define LAS __attribute__((address_space(3)))
; __device__ __forceinline__ void transpose_item(const float* W, int K, int N, bf16_t* WT, int kb, int nbd, int src0, LAS float* scr, int lane, const float* gk = nullptr) {
;     ...
;     for (int i = 0; i < 16; ++i) { if (gk) v[i] = v[i] * gk[k0 + 4 * i + (lane >> 4)];
;         LAS float* s = scr + (4 * i + (lane >> 4)) * 65 + (lane & 15) * 4; s[0] = v[i].x; s[1] = v[i].y; s[2] = v[i].z; s[3] = v[i].w; }
.LBB0_317:
	s_waitcnt vmcnt(13)
	v_add_u32_e32 v48, 0x820, v93
	ds_write2_b32 v48, v62, v63 offset1:1
	v_add_u32_e32 v48, 0x828, v93
	ds_write2_b32 v48, v60, v61 offset1:1
	v_add_u32_e32 v48, 0xc30, v93
	ds_write2_b32 v48, v56, v57 offset1:1
	v_add_u32_e32 v48, 0xc38, v93
	s_and_b64 vcc, exec, s[38:39]
	ds_write2_b32 v48, v58, v59 offset1:1
	s_cbranch_vccnz .LBB0_372
	v_mov_b32_e32 v48, v164
	v_mov_b32_e32 v56, v165
	s_waitcnt vmcnt(1)
	v_pk_mul_f32 v[52:53], v[42:43], v[48:49] op_sel_hi:[1,0]
	v_pk_mul_f32 v[54:55], v[40:41], v[48:49] op_sel_hi:[1,0]
	s_waitcnt vmcnt(0)
	v_pk_mul_f32 v[50:51], v[46:47], v[56:57] op_sel_hi:[1,0]
	v_pk_mul_f32 v[48:49], v[44:45], v[56:57] op_sel_hi:[1,0]
	s_cbranch_execnz .LBB0_320

; #define LAS __attribute__((address_space(3)))
; __device__ __forceinline__ void transpose_item(const float* W, int K, int N, bf16_t* WT, int kb, int nbd, int src0, LAS float* scr, int lane, const float* gk = nullptr) {
;     ...
;     for (int i = 0; i < 16; ++i) { if (gk) v[i] = v[i] * gk[k0 + 4 * i + (lane >> 4)];
;         LAS float* s = scr + (4 * i + (lane >> 4)) * 65 + (lane & 15) * 4; s[0] = v[i].x; s[1] = v[i].y; s[2] = v[i].z; s[3] = v[i].w; }
.LBB0_320:
	s_waitcnt vmcnt(11)
	v_add_u32_e32 v40, 0x1040, v93
	ds_write2_b32 v40, v54, v55 offset1:1
	v_add_u32_e32 v40, 0x1048, v93
	ds_write2_b32 v40, v52, v53 offset1:1
	v_add_u32_e32 v40, 0x1450, v93
	ds_write2_b32 v40, v48, v49 offset1:1
	v_add_u32_e32 v40, 0x1458, v93
	s_and_b64 vcc, exec, s[38:39]
	ds_write2_b32 v40, v50, v51 offset1:1
	s_cbranch_vccnz .LBB0_373
	v_mov_b32_e32 v40, v166
	v_mov_b32_e32 v48, v167
	s_waitcnt vmcnt(1)
	v_pk_mul_f32 v[44:45], v[34:35], v[40:41] op_sel_hi:[1,0]
	v_pk_mul_f32 v[46:47], v[32:33], v[40:41] op_sel_hi:[1,0]
	s_waitcnt vmcnt(0)
	v_pk_mul_f32 v[42:43], v[38:39], v[48:49] op_sel_hi:[1,0]
	v_pk_mul_f32 v[40:41], v[36:37], v[48:49] op_sel_hi:[1,0]
	s_cbranch_execnz .LBB0_323

; #define LAS __attribute__((address_space(3)))
; __device__ __forceinline__ void transpose_item(const float* W, int K, int N, bf16_t* WT, int kb, int nbd, int src0, LAS float* scr, int lane, const float* gk = nullptr) {
;     ...
;     for (int i = 0; i < 16; ++i) { if (gk) v[i] = v[i] * gk[k0 + 4 * i + (lane >> 4)];
;         LAS float* s = scr + (4 * i + (lane >> 4)) * 65 + (lane & 15) * 4; s[0] = v[i].x; s[1] = v[i].y; s[2] = v[i].z; s[3] = v[i].w; }
.LBB0_323:
	s_waitcnt vmcnt(9)
	v_add_u32_e32 v32, 0x1860, v93
	ds_write2_b32 v32, v46, v47 offset1:1
	v_add_u32_e32 v32, 0x1868, v93
	ds_write2_b32 v32, v44, v45 offset1:1
	v_add_u32_e32 v32, 0x1c70, v93
	ds_write2_b32 v32, v40, v41 offset1:1
	v_add_u32_e32 v32, 0x1c78, v93
	s_and_b64 vcc, exec, s[38:39]
	ds_write2_b32 v32, v42, v43 offset1:1
	s_cbranch_vccnz .LBB0_374
	v_mov_b32_e32 v32, v168
	v_mov_b32_e32 v40, v169
	s_waitcnt vmcnt(1)
	v_pk_mul_f32 v[36:37], v[26:27], v[32:33] op_sel_hi:[1,0]
	v_pk_mul_f32 v[38:39], v[24:25], v[32:33] op_sel_hi:[1,0]
	s_waitcnt vmcnt(0)
	v_pk_mul_f32 v[34:35], v[30:31], v[40:41] op_sel_hi:[1,0]
	v_pk_mul_f32 v[32:33], v[28:29], v[40:41] op_sel_hi:[1,0]
	s_cbranch_execnz .LBB0_326

; #define LAS __attribute__((address_space(3)))
; __device__ __forceinline__ void transpose_item(const float* W, int K, int N, bf16_t* WT, int kb, int nbd, int src0, LAS float* scr, int lane, const float* gk = nullptr) {
;     ...
;     for (int i = 0; i < 16; ++i) { if (gk) v[i] = v[i] * gk[k0 + 4 * i + (lane >> 4)];
;         LAS float* s = scr + (4 * i + (lane >> 4)) * 65 + (lane & 15) * 4; s[0] = v[i].x; s[1] = v[i].y; s[2] = v[i].z; s[3] = v[i].w; }
.LBB0_326:
	s_waitcnt vmcnt(7)
	v_add_u32_e32 v24, 0x2080, v93
	ds_write2_b32 v24, v38, v39 offset1:1
	v_add_u32_e32 v24, 0x2088, v93
	ds_write2_b32 v24, v36, v37 offset1:1
	v_add_u32_e32 v24, 0x2490, v93
	ds_write2_b32 v24, v32, v33 offset1:1
	v_add_u32_e32 v24, 0x2498, v93
	s_and_b64 vcc, exec, s[38:39]
	ds_write2_b32 v24, v34, v35 offset1:1
	s_cbranch_vccnz .LBB0_375
	v_mov_b32_e32 v24, v170
	v_mov_b32_e32 v32, v171
	s_waitcnt vmcnt(1)
	v_pk_mul_f32 v[28:29], v[18:19], v[24:25] op_sel_hi:[1,0]
	v_pk_mul_f32 v[30:31], v[16:17], v[24:25] op_sel_hi:[1,0]
	s_waitcnt vmcnt(0)
	v_pk_mul_f32 v[26:27], v[22:23], v[32:33] op_sel_hi:[1,0]
	v_pk_mul_f32 v[24:25], v[20:21], v[32:33] op_sel_hi:[1,0]
	s_cbranch_execnz .LBB0_329

; #define LAS __attribute__((address_space(3)))
; __device__ __forceinline__ void transpose_item(const float* W, int K, int N, bf16_t* WT, int kb, int nbd, int src0, LAS float* scr, int lane, const float* gk = nullptr) {
;     ...
;     for (int i = 0; i < 16; ++i) { if (gk) v[i] = v[i] * gk[k0 + 4 * i + (lane >> 4)];
;         LAS float* s = scr + (4 * i + (lane >> 4)) * 65 + (lane & 15) * 4; s[0] = v[i].x; s[1] = v[i].y; s[2] = v[i].z; s[3] = v[i].w; }
.LBB0_329:
	s_waitcnt vmcnt(5)
	v_add_u32_e32 v16, 0x28a0, v93
	ds_write2_b32 v16, v30, v31 offset1:1
	v_add_u32_e32 v16, 0x28a8, v93
	ds_write2_b32 v16, v28, v29 offset1:1
	v_add_u32_e32 v16, 0x2cb0, v93
	ds_write2_b32 v16, v24, v25 offset1:1
	v_add_u32_e32 v16, 0x2cb8, v93
	s_and_b64 vcc, exec, s[38:39]
	ds_write2_b32 v16, v26, v27 offset1:1
	s_cbranch_vccnz .LBB0_376
	v_mov_b32_e32 v16, v172
	v_mov_b32_e32 v24, v173
	s_waitcnt vmcnt(1)
	v_pk_mul_f32 v[20:21], v[10:11], v[16:17] op_sel_hi:[1,0]
	v_pk_mul_f32 v[22:23], v[8:9], v[16:17] op_sel_hi:[1,0]
	s_waitcnt vmcnt(0)
	v_pk_mul_f32 v[18:19], v[14:15], v[24:25] op_sel_hi:[1,0]
	v_pk_mul_f32 v[16:17], v[12:13], v[24:25] op_sel_hi:[1,0]
	s_cbranch_execnz .LBB0_332

; #define LAS __attribute__((address_space(3)))
; __device__ __forceinline__ void transpose_item(const float* W, int K, int N, bf16_t* WT, int kb, int nbd, int src0, LAS float* scr, int lane, const float* gk = nullptr) {
;     ...
;     for (int i = 0; i < 16; ++i) { if (gk) v[i] = v[i] * gk[k0 + 4 * i + (lane >> 4)];
;         LAS float* s = scr + (4 * i + (lane >> 4)) * 65 + (lane & 15) * 4; s[0] = v[i].x; s[1] = v[i].y; s[2] = v[i].z; s[3] = v[i].w; }
.LBB0_332:
	s_waitcnt vmcnt(3)
	v_add_u32_e32 v8, 0x30c0, v93
	ds_write2_b32 v8, v22, v23 offset1:1
	v_add_u32_e32 v8, 0x30c8, v93
	ds_write2_b32 v8, v20, v21 offset1:1
	v_add_u32_e32 v8, 0x34d0, v93
	ds_write2_b32 v8, v16, v17 offset1:1
	v_add_u32_e32 v8, 0x34d8, v93
	s_and_b64 vcc, exec, s[38:39]
	ds_write2_b32 v8, v18, v19 offset1:1
	s_cbranch_vccnz .LBB0_377
	v_mov_b32_e32 v8, v174
	v_mov_b32_e32 v16, v175
	s_waitcnt vmcnt(1)
	v_pk_mul_f32 v[12:13], v[2:3], v[8:9] op_sel_hi:[1,0]
	v_pk_mul_f32 v[14:15], v[0:1], v[8:9] op_sel_hi:[1,0]
	s_waitcnt vmcnt(0)
	v_pk_mul_f32 v[10:11], v[6:7], v[16:17] op_sel_hi:[1,0]
	v_pk_mul_f32 v[8:9], v[4:5], v[16:17] op_sel_hi:[1,0]
	s_cbranch_execnz .LBB0_335

; #define LAS __attribute__((address_space(3)))
; #define SCHED_FENCE() __builtin_amdgcn_sched_barrier(0)
; __device__ __forceinline__ void transpose_item(const float* W, int K, int N, bf16_t* WT, int kb, int nbd, int src0, LAS float* scr, int lane, const float* gk = nullptr) {
;     const int k0 = kb * 64;
;     const float* wp = W + (size_t)(k0 + (lane >> 4)) * N + src0 + (lane & 15) * 4;
;     f32x4 v[16];
; #pragma unroll
;     for (int i = 0; i < 16; ++i) v[i] = *(const f32x4*)(wp + (size_t)(4 * i) * N);
;     SCHED_FENCE();
; #pragma unroll
;     for (int i = 0; i < 16; ++i) { if (gk) v[i] = v[i] * gk[k0 + 4 * i + (lane >> 4)];
;         LAS float* s = scr + (4 * i + (lane >> 4)) * 65 + (lane & 15) * 4; s[0] = v[i].x; s[1] = v[i].y; s[2] = v[i].z; s[3] = v[i].w; }
.LBB0_337:
	s_andn2_b64 vcc, exec, s[6:7]
	s_cbranch_vccnz .LBB0_257
	s_mul_hi_i32 s6, s28, 0x2e8ba2e9
	s_lshr_b32 s7, s6, 31
	s_ashr_i32 s29, s6, 5
	s_add_i32 s29, s29, s7
	s_mul_i32 s7, s29, 0xffffea00
	s_and_b32 s6, s28, 3
	s_add_i32 s7, s10, s7
	s_and_b32 s7, s7, 0xffffff80
	s_lshl_b32 s8, s6, 6
	s_or_b32 s9, s7, s8
	s_add_i32 s7, s8, s7
	s_addk_i32 s7, 0x1580
	s_cmp_lt_u32 s6, 2
	s_cselect_b32 s8, s9, s7
	s_lshl_b32 s6, s29, 6
	v_or_b32_e32 v64, s6, v92
	v_mov_b64_e32 v[0:1], s[54:55]
	s_mov_b32 s0, 0xb000
	v_mad_i64_i32 v[0:1], s[30:31], v64, s0, v[0:1]
	s_ashr_i32 s9, s8, 31
	v_lshl_add_u64 v[0:1], s[8:9], 2, v[0:1]
	v_lshlrev_b32_e32 v144, 2, v70
	v_lshl_add_u64 v[0:1], v[0:1], 0, v[144:145]
	s_mov_b32 s0, 0x2c000
	v_add_co_u32_e32 v2, vcc, s0, v0
	s_mov_b32 s0, 0x58000
	s_nop 0
	v_addc_co_u32_e32 v3, vcc, 0, v1, vcc
	global_load_dwordx4 v[56:59], v[0:1], off nt
	global_load_dwordx4 v[60:63], v[2:3], off nt
	v_add_co_u32_e32 v2, vcc, s0, v0
	s_mov_b32 s0, 0x84000
	s_nop 0
	v_addc_co_u32_e32 v3, vcc, 0, v1, vcc
	v_add_co_u32_e32 v4, vcc, s0, v0
	s_mov_b32 s0, 0xb0000
	s_waitcnt lgkmcnt(0)
	v_addc_co_u32_e32 v5, vcc, 0, v1, vcc
	global_load_dwordx4 v[48:51], v[2:3], off nt
	global_load_dwordx4 v[52:55], v[4:5], off nt
	v_add_co_u32_e32 v2, vcc, s0, v0
	s_mov_b32 s0, 0xdc000
	s_nop 0
	v_addc_co_u32_e32 v3, vcc, 0, v1, vcc
	v_add_co_u32_e32 v4, vcc, s0, v0
	s_mov_b32 s0, 0x108000
	s_nop 0
	v_addc_co_u32_e32 v5, vcc, 0, v1, vcc
	global_load_dwordx4 v[40:43], v[2:3], off nt
	global_load_dwordx4 v[44:47], v[4:5], off nt
	v_add_co_u32_e32 v2, vcc, s0, v0
	s_mov_b32 s0, 0x134000
	s_nop 0
	v_addc_co_u32_e32 v3, vcc, 0, v1, vcc
	v_add_co_u32_e32 v4, vcc, s0, v0
	s_mov_b32 s0, 0x160000
	s_nop 0
	v_addc_co_u32_e32 v5, vcc, 0, v1, vcc
	global_load_dwordx4 v[32:35], v[2:3], off nt
	s_waitcnt lgkmcnt(0)
	global_load_dwordx4 v[36:39], v[4:5], off nt
	v_add_co_u32_e32 v2, vcc, s0, v0
	s_mov_b32 s0, 0x18c000
	s_nop 0
	v_addc_co_u32_e32 v3, vcc, 0, v1, vcc
	v_add_co_u32_e32 v4, vcc, s0, v0
	s_mov_b32 s0, 0x1b8000
	s_nop 0
	v_addc_co_u32_e32 v5, vcc, 0, v1, vcc
	global_load_dwordx4 v[24:27], v[2:3], off nt
	global_load_dwordx4 v[28:31], v[4:5], off nt
	v_add_co_u32_e32 v2, vcc, s0, v0
	s_mov_b32 s0, 0x1e4000
	s_nop 0
	v_addc_co_u32_e32 v3, vcc, 0, v1, vcc
	v_add_co_u32_e32 v4, vcc, s0, v0
	s_mov_b32 s0, 0x210000
	s_nop 0
	v_addc_co_u32_e32 v5, vcc, 0, v1, vcc
	global_load_dwordx4 v[16:19], v[2:3], off nt
	global_load_dwordx4 v[20:23], v[4:5], off nt
	v_add_co_u32_e32 v2, vcc, s0, v0
	v_ashrrev_i32_e32 v65, 31, v64
	s_nop 0
	v_addc_co_u32_e32 v3, vcc, 0, v1, vcc
	v_add_co_u32_e32 v4, vcc, 0x23c000, v0
	s_nop 1
	v_addc_co_u32_e32 v5, vcc, 0, v1, vcc
	global_load_dwordx4 v[8:11], v[2:3], off nt
	global_load_dwordx4 v[12:15], v[4:5], off nt
	v_add_co_u32_e32 v2, vcc, 0x268000, v0
	s_nop 1
	v_addc_co_u32_e32 v3, vcc, 0, v1, vcc
	v_add_co_u32_e32 v4, vcc, 0x294000, v0
	s_nop 1
	v_addc_co_u32_e32 v5, vcc, 0, v1, vcc
	global_load_dwordx4 v[0:3], v[2:3], off nt
	s_nop 0
	global_load_dwordx4 v[4:7], v[4:5], off nt
	v_readlane_b32 s0, v251, 24
	v_readlane_b32 s1, v251, 25
	s_andn2_b64 vcc, exec, s[0:1]
	v_lshl_add_u64 v[86:87], v[64:65], 2, s[52:53]
	v_cndmask_b32_e64 v66, 0, 1, s[0:1]
	v_cmp_ne_u32_e64 s[38:39], 1, v66
	s_cbranch_vccnz .LBB0_361
	global_load_dword v160, v[86:87], off
	global_load_dword v161, v[86:87], off offset:16
	global_load_dword v162, v[86:87], off offset:32
	global_load_dword v163, v[86:87], off offset:48
	global_load_dword v164, v[86:87], off offset:64
	global_load_dword v165, v[86:87], off offset:80
	global_load_dword v166, v[86:87], off offset:96
	global_load_dword v167, v[86:87], off offset:112
	global_load_dword v168, v[86:87], off offset:128
	global_load_dword v169, v[86:87], off offset:144
	global_load_dword v170, v[86:87], off offset:160
	global_load_dword v171, v[86:87], off offset:176
	global_load_dword v172, v[86:87], off offset:192
	global_load_dword v173, v[86:87], off offset:208
	global_load_dword v174, v[86:87], off offset:224
	global_load_dword v175, v[86:87], off offset:240
	s_waitcnt vmcnt(0)
	v_mov_b32_e32 v64, v160
	v_mov_b32_e32 v104, v161
	s_waitcnt vmcnt(1)
	v_pk_mul_f32 v[88:89], v[58:59], v[64:65] op_sel_hi:[1,0]
	v_pk_mul_f32 v[90:91], v[56:57], v[64:65] op_sel_hi:[1,0]
	s_waitcnt vmcnt(0)
	v_pk_mul_f32 v[66:67], v[62:63], v[104:105] op_sel_hi:[1,0]
	v_pk_mul_f32 v[64:65], v[60:61], v[104:105] op_sel_hi:[1,0]
	s_cbranch_execnz .LBB0_341

; #define LAS __attribute__((address_space(3)))
; __device__ __forceinline__ void transpose_item(const float* W, int K, int N, bf16_t* WT, int kb, int nbd, int src0, LAS float* scr, int lane, const float* gk = nullptr) {
;     ...
;     for (int i = 0; i < 16; ++i) { if (gk) v[i] = v[i] * gk[k0 + 4 * i + (lane >> 4)];
;         LAS float* s = scr + (4 * i + (lane >> 4)) * 65 + (lane & 15) * 4; s[0] = v[i].x; s[1] = v[i].y; s[2] = v[i].z; s[3] = v[i].w; }
.LBB0_341:
	s_waitcnt vmcnt(15)
	v_add_u32_e32 v56, 0x410, v93
	ds_write2_b32 v93, v90, v91 offset1:1
	ds_write2_b32 v93, v88, v89 offset0:2 offset1:3
	ds_write2_b32 v56, v64, v65 offset1:1
	v_add_u32_e32 v56, 0x418, v93
	s_and_b64 vcc, exec, s[38:39]
	ds_write2_b32 v56, v66, v67 offset1:1
	s_cbranch_vccnz .LBB0_362
	v_mov_b32_e32 v56, v162
	v_mov_b32_e32 v64, v163
	s_waitcnt vmcnt(1)
	v_pk_mul_f32 v[60:61], v[50:51], v[56:57] op_sel_hi:[1,0]
	v_pk_mul_f32 v[62:63], v[48:49], v[56:57] op_sel_hi:[1,0]
	s_waitcnt vmcnt(0)
	v_pk_mul_f32 v[58:59], v[54:55], v[64:65] op_sel_hi:[1,0]
	v_pk_mul_f32 v[56:57], v[52:53], v[64:65] op_sel_hi:[1,0]
	s_cbranch_execnz .LBB0_344

; #define LAS __attribute__((address_space(3)))
; __device__ __forceinline__ void transpose_item(const float* W, int K, int N, bf16_t* WT, int kb, int nbd, int src0, LAS float* scr, int lane, const float* gk = nullptr) {
;     ...
;     for (int i = 0; i < 16; ++i) { if (gk) v[i] = v[i] * gk[k0 + 4 * i + (lane >> 4)];
;         LAS float* s = scr + (4 * i + (lane >> 4)) * 65 + (lane & 15) * 4; s[0] = v[i].x; s[1] = v[i].y; s[2] = v[i].z; s[3] = v[i].w; }
.LBB0_359:
	s_waitcnt vmcnt(3)
	v_add_u32_e32 v8, 0x30c0, v93
	ds_write2_b32 v8, v22, v23 offset1:1
	v_add_u32_e32 v8, 0x30c8, v93
	ds_write2_b32 v8, v20, v21 offset1:1
	v_add_u32_e32 v8, 0x34d0, v93
	ds_write2_b32 v8, v16, v17 offset1:1
	v_add_u32_e32 v8, 0x34d8, v93
	s_and_b64 vcc, exec, s[38:39]
	ds_write2_b32 v8, v18, v19 offset1:1
	s_cbranch_vccnz .LBB0_368
	v_mov_b32_e32 v8, v174
	v_mov_b32_e32 v16, v175
	s_waitcnt vmcnt(1)
	v_pk_mul_f32 v[12:13], v[2:3], v[8:9] op_sel_hi:[1,0]
	v_pk_mul_f32 v[14:15], v[0:1], v[8:9] op_sel_hi:[1,0]
	s_waitcnt vmcnt(0)
	v_pk_mul_f32 v[10:11], v[6:7], v[16:17] op_sel_hi:[1,0]
	v_pk_mul_f32 v[8:9], v[4:5], v[16:17] op_sel_hi:[1,0]
	s_cbranch_execnz .LBB0_256
	s_branch .LBB0_369
